# adds latent-first (longest-first) ordering of hyena work-queue units
# speedup vs baseline: 1.0073x; 1.0073x over previous
.LBB0_587:
	s_or_b64 exec, exec, s[0:1]
	s_add_i32 s0, 0, 0x20008
	v_mov_b32_e32 v1, s0
	s_waitcnt lgkmcnt(0)
	s_barrier
	ds_read_b32 v1, v1
	s_movk_i32 s1, 0x7ff
	s_movk_i32 s0, 0x800
	s_mov_b32 s3, 0
	s_waitcnt lgkmcnt(0)
	v_cmp_lt_u32_e32 vcc, s1, v1
	v_readfirstlane_b32 s17, v1
	v_cmp_gt_u32_e64 s[4:5], s0, v1
	s_barrier
	s_cbranch_vccnz .LBB0_603
	s_lshr_b32 s0, s17, 10
	s_xor_b32 s0, s0, 1
	s_and_b32 s2, s0, 1
	s_and_b32 s10, s17, 0x3ff
	s_cmp_eq_u32 s2, 0
	s_cselect_b64 s[0:1], -1, 0
	s_movk_i32 s8, 0x100
	s_and_b64 s[6:7], s[0:1], exec
	s_cselect_b32 s11, s8, 0x400
	v_mov_b32_e32 v16, v154
	s_add_i32 s8, s11, -1
	s_lshl_b32 s2, s2, 13
	s_add_u32 s6, s90, s2
	v_lshlrev_b32_e32 v6, 3, v16
	s_addc_u32 s7, s91, 0
	v_ashrrev_i32_e32 v7, 31, v6
	v_lshl_add_u64 v[2:3], v[6:7], 1, s[6:7]
	s_lshl_b32 s2, s10, 14
	v_lshl_add_u64 v[8:9], v[2:3], 0, s[2:3]
	v_add_co_u32_e32 v2, vcc, 0x21918000, v8
	v_and_b32_e32 v6, s8, v6
	s_nop 0
	v_addc_co_u32_e32 v3, vcc, 0, v9, vcc
	global_load_dwordx4 v[2:5], v[2:3], off
	s_mov_b64 s[2:3], 0x21918000
	v_cmp_ne_u32_e64 s[6:7], 0, v6
	v_lshl_add_u64 v[14:15], v[8:9], 0, s[2:3]
	v_mov_b32_e32 v80, 0
	v_mov_b32_e32 v1, 0
	s_and_saveexec_b64 s[2:3], s[6:7]
	s_cbranch_execz .LBB0_590
	global_load_ushort v1, v[14:15], off offset:-2

.LBB0_607:
	s_lshr_b32 s0, s17, 10
	s_xor_b32 s0, s0, 1
	s_and_b32 s0, s0, 1
	s_and_b32 s16, s17, 0x3ff
	s_cmp_eq_u32 s0, 0
	s_mov_b64 s[0:1], -1
	s_cbranch_scc1 .LBB0_668
	v_mov_b32_e32 v22, v154
	v_mov_b32_e32 v95, 0
	v_cmp_eq_u32_e32 vcc, 0, v22
	s_and_saveexec_b64 s[0:1], vcc
	s_cbranch_execz .LBB0_612
	s_mov_b64 s[4:5], exec
	v_mbcnt_lo_u32_b32 v15, s4, 0
	v_mbcnt_hi_u32_b32 v15, s5, v15
	v_cmp_eq_u32_e32 vcc, 0, v15
	s_and_saveexec_b64 s[2:3], vcc
	s_cbranch_execz .LBB0_611
	s_bcnt1_i32_b64 s4, s[4:5]
	v_mov_b32_e32 v16, s4
	v_readlane_b32 s4, v232, 2
	v_readlane_b32 s5, v232, 3
	s_nop 4
	global_atomic_add v16, v14, v16, s[4:5] sc0

.LBB0_649:
	s_or_b64 exec, exec, s[6:7]
	s_waitcnt lgkmcnt(0)
	s_barrier
	s_andn2_b64 vcc, exec, s[4:5]
	s_cbranch_vccnz .LBB0_640
	v_mov_b32_e32 v15, s44
	ds_read_b32 v15, v15
	s_waitcnt lgkmcnt(0)
	v_cmp_lt_u32_e32 vcc, s45, v15
	v_readfirstlane_b32 s17, v15
	s_cbranch_vccnz .LBB0_640
	s_lshr_b32 s4, s17, 10
	s_xor_b32 s4, s4, 1
	s_and_b32 s6, s4, 1
	s_and_b32 s20, s17, 0x3ff
	s_cmp_eq_u32 s6, 0
	s_cselect_b64 s[8:9], -1, 0
	s_and_b64 s[4:5], s[8:9], exec
	s_cselect_b32 s21, s46, 0x400
	v_mov_b32_e32 v40, v154
	s_add_i32 s7, s21, -1
	s_lshl_b32 s4, s6, 13
	s_add_u32 s4, s24, s4
	v_lshlrev_b32_e32 v28, 3, v40
	s_addc_u32 s5, s25, 0
	v_ashrrev_i32_e32 v29, 31, v28
	v_lshl_add_u64 v[16:17], v[28:29], 1, s[4:5]
	s_lshl_b32 s10, s20, 14
	v_lshl_add_u64 v[16:17], v[16:17], 0, s[10:11]
	global_load_dwordx4 v[24:27], v[16:17], off
	v_and_b32_e32 v15, s7, v28
	v_cmp_ne_u32_e64 s[6:7], 0, v15
	v_mov_b32_e32 v96, 0
	v_mov_b32_e32 v97, 0
	s_and_saveexec_b64 s[4:5], s[6:7]
	s_cbranch_execz .LBB0_653
	global_load_ushort v97, v[16:17], off offset:-2

.LBB0_712:
	s_or_b64 exec, exec, s[6:7]
	s_waitcnt lgkmcnt(0)
	s_barrier
	s_andn2_b64 vcc, exec, s[4:5]
	s_cbranch_vccnz .LBB0_701
	v_mov_b32_e32 v15, s44
	ds_read_b32 v15, v15
	s_waitcnt lgkmcnt(0)
	v_cmp_lt_u32_e32 vcc, s45, v15
	v_readfirstlane_b32 s17, v15
	s_cbranch_vccnz .LBB0_701
	s_lshr_b32 s4, s17, 10
	s_xor_b32 s4, s4, 1
	s_and_b32 s6, s4, 1
	s_and_b32 s20, s17, 0x3ff
	s_cmp_eq_u32 s6, 0
	s_cselect_b64 s[8:9], -1, 0
	s_and_b64 s[4:5], s[8:9], exec
	s_cselect_b32 s21, s46, 0x400
	v_mov_b32_e32 v24, v154
	s_add_i32 s7, s21, -1
	s_lshl_b32 s4, s6, 13
	s_add_u32 s4, s24, s4
	v_lshlrev_b32_e32 v6, 3, v24
	s_addc_u32 s5, s25, 0
	v_ashrrev_i32_e32 v7, 31, v6
	v_lshl_add_u64 v[2:3], v[6:7], 1, s[4:5]
	s_lshl_b32 s10, s20, 14
	v_lshl_add_u64 v[16:17], v[2:3], 0, s[10:11]
	global_load_dwordx4 v[2:5], v[16:17], off
	v_and_b32_e32 v6, s7, v6
	v_cmp_ne_u32_e64 s[6:7], 0, v6
	v_mov_b32_e32 v80, 0
	v_mov_b32_e32 v1, 0
	s_and_saveexec_b64 s[4:5], s[6:7]
	s_cbranch_execz .LBB0_716
	global_load_ushort v1, v[16:17], off offset:-2

.LBB0_1828:
	s_or_b64 exec, exec, s[0:1]
	s_add_i32 s0, 0, 0x20008
	v_mov_b32_e32 v1, s0
	s_waitcnt lgkmcnt(0)
	s_barrier
	ds_read_b32 v1, v1
	s_movk_i32 s1, 0x7ff
	s_movk_i32 s0, 0x800
	s_mov_b32 s3, 0
	s_waitcnt lgkmcnt(0)
	v_cmp_lt_u32_e32 vcc, s1, v1
	v_readfirstlane_b32 s19, v1
	v_cmp_gt_u32_e64 s[4:5], s0, v1
	s_barrier
	s_cbranch_vccnz .LBB0_1844
	s_lshr_b32 s0, s19, 10
	s_xor_b32 s0, s0, 1
	s_and_b32 s2, s0, 1
	s_and_b32 s12, s19, 0x3ff
	s_cmp_eq_u32 s2, 0
	s_cselect_b64 s[0:1], -1, 0
	s_movk_i32 s8, 0x100
	s_and_b64 s[6:7], s[0:1], exec
	s_cselect_b32 s13, s8, 0x400
	v_mov_b32_e32 v16, v154
	s_add_i32 s8, s13, -1
	s_lshl_b32 s2, s2, 13
	s_add_u32 s6, s90, s2
	v_lshlrev_b32_e32 v6, 3, v16
	s_addc_u32 s7, s91, 0
	v_ashrrev_i32_e32 v7, 31, v6
	v_lshl_add_u64 v[2:3], v[6:7], 1, s[6:7]
	s_lshl_b32 s2, s12, 14
	v_lshl_add_u64 v[8:9], v[2:3], 0, s[2:3]
	v_add_co_u32_e32 v2, vcc, 0x21918000, v8
	v_and_b32_e32 v6, s8, v6
	s_nop 0
	v_addc_co_u32_e32 v3, vcc, 0, v9, vcc
	global_load_dwordx4 v[2:5], v[2:3], off
	s_mov_b64 s[2:3], 0x21918000
	v_cmp_ne_u32_e64 s[6:7], 0, v6
	v_lshl_add_u64 v[14:15], v[8:9], 0, s[2:3]
	v_mov_b32_e32 v80, 0
	v_mov_b32_e32 v1, 0
	s_and_saveexec_b64 s[2:3], s[6:7]
	s_cbranch_execz .LBB0_1831
	global_load_ushort v1, v[14:15], off offset:-2

.LBB0_1848:
	s_lshr_b32 s0, s19, 10
	s_xor_b32 s0, s0, 1
	s_and_b32 s0, s0, 1
	s_and_b32 s18, s19, 0x3ff
	s_cmp_eq_u32 s0, 0
	s_mov_b64 s[0:1], -1
	s_cbranch_scc1 .LBB0_1909
	v_mov_b32_e32 v22, v154
	v_mov_b32_e32 v102, 0
	v_cmp_eq_u32_e32 vcc, 0, v22
	s_and_saveexec_b64 s[0:1], vcc
	s_cbranch_execz .LBB0_1853
	s_mov_b64 s[4:5], exec
	v_mbcnt_lo_u32_b32 v15, s4, 0
	v_mbcnt_hi_u32_b32 v15, s5, v15
	v_cmp_eq_u32_e32 vcc, 0, v15
	s_and_saveexec_b64 s[2:3], vcc
	s_cbranch_execz .LBB0_1852
	s_bcnt1_i32_b64 s4, s[4:5]
	v_mov_b32_e32 v16, s4
	global_atomic_add v16, v14, v16, s[10:11] sc0

.LBB0_1890:
	s_or_b64 exec, exec, s[6:7]
	s_waitcnt lgkmcnt(0)
	s_barrier
	s_andn2_b64 vcc, exec, s[4:5]
	s_cbranch_vccnz .LBB0_1881
	v_mov_b32_e32 v15, s46
	ds_read_b32 v15, v15
	s_waitcnt lgkmcnt(0)
	v_cmp_lt_u32_e32 vcc, s47, v15
	v_readfirstlane_b32 s19, v15
	s_cbranch_vccnz .LBB0_1881
	s_lshr_b32 s4, s19, 10
	s_xor_b32 s4, s4, 1
	s_and_b32 s6, s4, 1
	s_and_b32 s22, s19, 0x3ff
	s_cmp_eq_u32 s6, 0
	s_cselect_b64 s[8:9], -1, 0
	s_and_b64 s[4:5], s[8:9], exec
	s_cselect_b32 s23, s48, 0x400
	v_mov_b32_e32 v40, v154
	s_add_i32 s7, s23, -1
	s_lshl_b32 s4, s6, 13
	s_add_u32 s4, s26, s4
	v_lshlrev_b32_e32 v28, 3, v40
	s_addc_u32 s5, s27, 0
	v_ashrrev_i32_e32 v29, 31, v28
	v_lshl_add_u64 v[16:17], v[28:29], 1, s[4:5]
	s_lshl_b32 s12, s22, 14
	v_lshl_add_u64 v[16:17], v[16:17], 0, s[12:13]
	global_load_dwordx4 v[24:27], v[16:17], off
	v_and_b32_e32 v15, s7, v28
	v_cmp_ne_u32_e64 s[6:7], 0, v15
	v_mov_b32_e32 v103, 0
	v_mov_b32_e32 v104, 0
	s_and_saveexec_b64 s[4:5], s[6:7]
	s_cbranch_execz .LBB0_1894
	global_load_ushort v104, v[16:17], off offset:-2

.LBB0_1953:
	s_or_b64 exec, exec, s[6:7]
	s_waitcnt lgkmcnt(0)
	s_barrier
	s_andn2_b64 vcc, exec, s[4:5]
	s_cbranch_vccnz .LBB0_1942
	v_mov_b32_e32 v15, s46
	ds_read_b32 v15, v15
	s_waitcnt lgkmcnt(0)
	v_cmp_lt_u32_e32 vcc, s47, v15
	v_readfirstlane_b32 s19, v15
	s_cbranch_vccnz .LBB0_1942
	s_lshr_b32 s4, s19, 10
	s_xor_b32 s4, s4, 1
	s_and_b32 s6, s4, 1
	s_and_b32 s22, s19, 0x3ff
	s_cmp_eq_u32 s6, 0
	s_cselect_b64 s[8:9], -1, 0
	s_and_b64 s[4:5], s[8:9], exec
	s_cselect_b32 s23, s48, 0x400
	v_mov_b32_e32 v24, v154
	s_add_i32 s7, s23, -1
	s_lshl_b32 s4, s6, 13
	s_add_u32 s4, s26, s4
	v_lshlrev_b32_e32 v6, 3, v24
	s_addc_u32 s5, s27, 0
	v_ashrrev_i32_e32 v7, 31, v6
	v_lshl_add_u64 v[2:3], v[6:7], 1, s[4:5]
	s_lshl_b32 s12, s22, 14
	v_lshl_add_u64 v[16:17], v[2:3], 0, s[12:13]
	global_load_dwordx4 v[2:5], v[16:17], off
	v_and_b32_e32 v6, s7, v6
	v_cmp_ne_u32_e64 s[6:7], 0, v6
	v_mov_b32_e32 v80, 0
	v_mov_b32_e32 v1, 0
	s_and_saveexec_b64 s[4:5], s[6:7]
	s_cbranch_execz .LBB0_1957
	global_load_ushort v1, v[16:17], off offset:-2
